# v37 + EpiRes epilogues (w_out, ff2): the four exec-masked per-row sum-of-squares dword stores of each half replaced by one full-wave store (lane group fq stores row group m=fq)
# baseline (speedup 1.0000x reference)
; __device__ __forceinline__ float shx(float v, int lane, int o) { return __int_as_float(__builtin_amdgcn_ds_bpermute((lane ^ o) << 2, __float_as_int(v))); }
; __device__ __forceinline__ u32x4 pack8(const f32x4 a, const f32x4 b) { u32x4 w; w.x = cvt_pk_bf16(a[0], a[1]); w.y = cvt_pk_bf16(a[2], a[3]); w.z = cvt_pk_bf16(b[0], b[1]); w.w = cvt_pk_bf16(b[2], b[3]); return w; }
; __device__ __forceinline__ void unpack8(const u32x4 w, f32x4& a, f32x4& b) { a = (f32x4){bflo(w.x), bfhi(w.x), bflo(w.y), bfhi(w.y)}; b = (f32x4){bflo(w.z), bfhi(w.z), bflo(w.w), bfhi(w.w)}; }
;     __device__ __forceinline__ void operator()(const Acc& acc, const Unit& u, int wr, int wc, int fr, int fq) const {
;     ...
;         for (int ai = 0; ai < 2; ++ai) {
;             u32x4 hv[4][2];
; #pragma unroll
;             for (int m = 0; m < 4; ++m)
; #pragma unroll
;                 for (int bj = 0; bj < 2; ++bj) hv[m][bj] = *(const u32x4*)(hb + (size_t)(row0 + ai * 128 + m * 16) * DM + col0 + bj * 128);
; #pragma unroll
;             for (int m = 0; m < 4; ++m) { const size_t row = (size_t)(row0 + ai * 128 + m * 16); float sq = 0.f;
; #pragma unroll
;                 for (int bj = 0; bj < 2; ++bj) { f32x4 o0, o1; unpack8(hv[m][bj], o0, o1); o0 += acc[ai][bj][m][0] * sc; o1 += acc[ai][bj][m][1] * sc;
;                     *(u32x4*)(hb + row * DM + col0 + bj * 128) = pack8(o0, o1);
;                     sq += ((o0[0] * o0[0] + o0[1] * o0[1]) + (o0[2] * o0[2] + o0[3] * o0[3])) + ((o1[0] * o1[0] + o1[1] * o1[1]) + (o1[2] * o1[2] + o1[3] * o1[3])); }
;                 const int lane = fq * 16 + fr; sq += shx(sq, lane, 16); sq += shx(sq, lane, 32);
;                 if (fq == 0) ssq[row * 16 + u.pn * 4 + wc] = sq; } }
.LBB0_66:
.LBB0_67:
	v_lshl_add_u32 v172, s30, 8, v130
	v_lshlrev_b32_e32 v130, 2, v133
	v_lshlrev_b64 v[202:203], 1, v[168:169]
	v_ashrrev_i32_e32 v173, 31, v172
	v_lshl_add_u32 v130, v132, 6, v130
	v_lshl_add_u64 v[170:171], s[36:37], 0, v[202:203]
	v_lshlrev_b64 v[204:205], 11, v[172:173]
	v_xor_b32_e32 v191, 64, v130
	v_xor_b32_e32 v190, 0x80, v130
	v_lshl_add_u64 v[130:131], v[170:171], 0, v[204:205]
	global_load_dwordx4 v[192:195], v[130:131], off
	global_load_dwordx4 v[154:157], v[130:131], off offset:256
	v_add_u32_e32 v182, 16, v172
	v_ashrrev_i32_e32 v183, 31, v182
	v_add_u32_e32 v178, 32, v172
	v_lshlrev_b64 v[184:185], 11, v[182:183]
	v_ashrrev_i32_e32 v179, 31, v178
	v_add_u32_e32 v174, 48, v172
	v_lshl_add_u64 v[130:131], v[170:171], 0, v[184:185]
	v_lshlrev_b64 v[180:181], 11, v[178:179]
	v_ashrrev_i32_e32 v175, 31, v174
	global_load_dwordx4 v[150:153], v[130:131], off
	global_load_dwordx4 v[146:149], v[130:131], off offset:256
	v_lshl_add_u64 v[130:131], v[170:171], 0, v[180:181]
	v_lshlrev_b64 v[176:177], 11, v[174:175]
	global_load_dwordx4 v[142:145], v[130:131], off
	global_load_dwordx4 v[138:141], v[130:131], off offset:256
	v_lshl_add_u64 v[130:131], v[170:171], 0, v[176:177]
	v_cmp_eq_u32_e32 vcc, 0, v132
	global_load_dwordx4 v[134:137], v[130:131], off
	s_nop 0
	global_load_dwordx4 v[130:133], v[130:131], off offset:256
	v_lshl_add_u64 v[204:205], s[36:37], 0, v[204:205]
	v_lshl_add_u64 v[202:203], v[204:205], 0, v[202:203]
	s_waitcnt vmcnt(7)
	v_lshlrev_b32_e32 v206, 16, v192
	v_and_b32_e32 v207, 0xffff0000, v192
	v_lshlrev_b32_e32 v192, 16, v193
	v_and_b32_e32 v193, 0xffff0000, v193
	v_lshlrev_b32_e32 v208, 16, v194
	v_and_b32_e32 v209, 0xffff0000, v194
	v_lshlrev_b32_e32 v194, 16, v195
	v_and_b32_e32 v195, 0xffff0000, v195
	v_pk_add_f32 v[128:129], v[128:129], v[192:193]
	v_pk_add_f32 v[126:127], v[126:127], v[206:207]
	v_pk_add_f32 v[192:193], v[124:125], v[194:195]
	v_pk_add_f32 v[194:195], v[122:123], v[208:209]
	v_cvt_pk_bf16_f32 v122, v126, v127
	v_cvt_pk_bf16_f32 v123, v128, v129
	v_cvt_pk_bf16_f32 v124, v194, v195
	v_cvt_pk_bf16_f32 v125, v192, v193
	global_store_dwordx4 v[202:203], v[122:125], off
	s_nop 1
	v_mul_f32_e32 v122, v127, v127
	v_mul_f32_e32 v123, v129, v129
	v_fmac_f32_e32 v122, v126, v126
	v_fmac_f32_e32 v123, v128, v128
	v_add_f32_e32 v122, v122, v123
	v_mul_f32_e32 v123, v195, v195
	v_mul_f32_e32 v124, v193, v193
	v_fmac_f32_e32 v123, v194, v194
	v_fmac_f32_e32 v124, v192, v192
	v_add_f32_e32 v123, v123, v124
	v_add_f32_e32 v192, v122, v123
	s_waitcnt vmcnt(7)
	v_lshlrev_b32_e32 v122, 16, v154
	v_and_b32_e32 v123, 0xffff0000, v154
	v_lshlrev_b32_e32 v124, 16, v155
	v_and_b32_e32 v125, 0xffff0000, v155
	v_lshlrev_b32_e32 v126, 16, v156
	v_and_b32_e32 v127, 0xffff0000, v156
	v_lshlrev_b32_e32 v128, 16, v157
	v_and_b32_e32 v129, 0xffff0000, v157
	v_pk_add_f32 v[120:121], v[120:121], v[124:125]
	v_pk_add_f32 v[118:119], v[118:119], v[122:123]
	v_pk_add_f32 v[122:123], v[116:117], v[128:129]
	v_pk_add_f32 v[124:125], v[114:115], v[126:127]
	v_cvt_pk_bf16_f32 v114, v118, v119
	v_cvt_pk_bf16_f32 v115, v120, v121
	v_cvt_pk_bf16_f32 v116, v124, v125
	v_cvt_pk_bf16_f32 v117, v122, v123
	global_store_dwordx4 v[202:203], v[114:117], off offset:256
	s_nop 1
	v_mul_f32_e32 v114, v119, v119
	v_mul_f32_e32 v115, v121, v121
	v_fmac_f32_e32 v114, v118, v118
	v_fmac_f32_e32 v115, v120, v120
	v_add_f32_e32 v114, v114, v115
	v_mul_f32_e32 v115, v125, v125
	v_mul_f32_e32 v116, v123, v123
	v_fmac_f32_e32 v115, v124, v124
	v_fmac_f32_e32 v116, v122, v122
	v_add_f32_e32 v115, v115, v116
	v_add_f32_e32 v114, v114, v115
	v_add_f32_e32 v114, v192, v114
	ds_bpermute_b32 v115, v191, v114
	s_waitcnt lgkmcnt(0)
	v_add_f32_e32 v114, v114, v115
	ds_bpermute_b32 v115, v190, v114
	s_waitcnt lgkmcnt(0)
	v_add_f32_e32 v210, v114, v115
	s_waitcnt vmcnt(7)
	v_lshlrev_b32_e32 v114, 16, v150
	s_waitcnt lgkmcnt(0)
	v_and_b32_e32 v115, 0xffff0000, v150
	v_lshlrev_b32_e32 v116, 16, v151
	v_and_b32_e32 v117, 0xffff0000, v151
	v_lshlrev_b32_e32 v118, 16, v152
	v_and_b32_e32 v119, 0xffff0000, v152
	v_pk_add_f32 v[110:111], v[110:111], v[114:115]
	v_pk_add_f32 v[112:113], v[112:113], v[116:117]
	v_pk_add_f32 v[116:117], v[106:107], v[118:119]
	v_cvt_pk_bf16_f32 v106, v110, v111
	v_mul_f32_e32 v111, v111, v111
	v_lshlrev_b32_e32 v120, 16, v153
	v_and_b32_e32 v121, 0xffff0000, v153
	v_fmac_f32_e32 v111, v110, v110
	v_mul_f32_e32 v110, v113, v113
	v_pk_add_f32 v[114:115], v[108:109], v[120:121]
	v_fmac_f32_e32 v110, v112, v112
	v_cvt_pk_bf16_f32 v107, v112, v113
	v_add_f32_e32 v110, v111, v110
	v_mul_f32_e32 v111, v117, v117
	v_mul_f32_e32 v112, v115, v115
	v_fmac_f32_e32 v111, v116, v116
	v_fmac_f32_e32 v112, v114, v114
	v_add_f32_e32 v111, v111, v112
	v_add_f32_e32 v118, v110, v111
	s_waitcnt vmcnt(6)
	v_lshlrev_b32_e32 v110, 16, v146
	v_and_b32_e32 v111, 0xffff0000, v146
	v_lshlrev_b32_e32 v112, 16, v147
	v_and_b32_e32 v113, 0xffff0000, v147
	v_cvt_pk_bf16_f32 v109, v114, v115
	v_lshlrev_b32_e32 v114, 16, v148
	v_and_b32_e32 v115, 0xffff0000, v148
	v_pk_add_f32 v[104:105], v[104:105], v[112:113]
	v_pk_add_f32 v[102:103], v[102:103], v[110:111]
	v_cvt_pk_bf16_f32 v108, v116, v117
	v_lshlrev_b32_e32 v116, 16, v149
	v_and_b32_e32 v117, 0xffff0000, v149
	v_pk_add_f32 v[112:113], v[98:99], v[114:115]
	v_mul_f32_e32 v98, v103, v103
	v_mul_f32_e32 v99, v105, v105
	v_pk_add_f32 v[110:111], v[100:101], v[116:117]
	v_fmac_f32_e32 v98, v102, v102
	v_fmac_f32_e32 v99, v104, v104
	v_add_f32_e32 v98, v98, v99
	v_mul_f32_e32 v99, v113, v113
	v_mul_f32_e32 v100, v111, v111
	v_fmac_f32_e32 v99, v112, v112
	v_fmac_f32_e32 v100, v110, v110
	v_add_f32_e32 v99, v99, v100
	v_add_f32_e32 v98, v98, v99
	v_add_f32_e32 v101, v118, v98
	ds_bpermute_b32 v116, v191, v101
	v_lshl_add_u64 v[98:99], s[36:37], 0, v[184:185]
	v_lshl_add_u64 v[114:115], v[168:169], 1, v[98:99]
	v_cvt_pk_bf16_f32 v100, v102, v103
	v_cvt_pk_bf16_f32 v102, v112, v113
	s_waitcnt lgkmcnt(0)
; __device__ __forceinline__ float shx(float v, int lane, int o) { return __int_as_float(__builtin_amdgcn_ds_bpermute((lane ^ o) << 2, __float_as_int(v))); }
; __device__ __forceinline__ u32x4 pack8(const f32x4 a, const f32x4 b) { u32x4 w; w.x = cvt_pk_bf16(a[0], a[1]); w.y = cvt_pk_bf16(a[2], a[3]); w.z = cvt_pk_bf16(b[0], b[1]); w.w = cvt_pk_bf16(b[2], b[3]); return w; }
; __device__ __forceinline__ void unpack8(const u32x4 w, f32x4& a, f32x4& b) { a = (f32x4){bflo(w.x), bfhi(w.x), bflo(w.y), bfhi(w.y)}; b = (f32x4){bflo(w.z), bfhi(w.z), bflo(w.w), bfhi(w.w)}; }
;     __device__ __forceinline__ void operator()(const Acc& acc, const Unit& u, int wr, int wc, int fr, int fq) const {
;     ...
;         for (int ai = 0; ai < 2; ++ai) {
;             u32x4 hv[4][2];
; #pragma unroll
;             for (int m = 0; m < 4; ++m)
; #pragma unroll
;                 for (int bj = 0; bj < 2; ++bj) hv[m][bj] = *(const u32x4*)(hb + (size_t)(row0 + ai * 128 + m * 16) * DM + col0 + bj * 128);
; #pragma unroll
;             for (int m = 0; m < 4; ++m) { const size_t row = (size_t)(row0 + ai * 128 + m * 16); float sq = 0.f;
; #pragma unroll
;                 for (int bj = 0; bj < 2; ++bj) { f32x4 o0, o1; unpack8(hv[m][bj], o0, o1); o0 += acc[ai][bj][m][0] * sc; o1 += acc[ai][bj][m][1] * sc;
;                     *(u32x4*)(hb + row * DM + col0 + bj * 128) = pack8(o0, o1);
;                     sq += ((o0[0] * o0[0] + o0[1] * o0[1]) + (o0[2] * o0[2] + o0[3] * o0[3])) + ((o1[0] * o1[0] + o1[1] * o1[1]) + (o1[2] * o1[2] + o1[3] * o1[3])); }
;                 const int lane = fq * 16 + fr; sq += shx(sq, lane, 16); sq += shx(sq, lane, 32);
;                 if (fq == 0) ssq[row * 16 + u.pn * 4 + wc] = sq; } }
	v_add_f32_e32 v98, v101, v116
	ds_bpermute_b32 v99, v190, v98
	v_cvt_pk_bf16_f32 v101, v104, v105
	v_cvt_pk_bf16_f32 v103, v110, v111
	global_store_dwordx4 v[114:115], v[106:109], off
	global_store_dwordx4 v[114:115], v[100:103], off offset:256
	s_waitcnt lgkmcnt(0)
	v_add_f32_e32 v211, v98, v99
	s_waitcnt vmcnt(7)
	v_lshlrev_b32_e32 v98, 16, v142
	s_waitcnt lgkmcnt(0)
	v_and_b32_e32 v99, 0xffff0000, v142
	v_lshlrev_b32_e32 v100, 16, v143
	v_and_b32_e32 v101, 0xffff0000, v143
	v_lshlrev_b32_e32 v102, 16, v144
	v_and_b32_e32 v103, 0xffff0000, v144
	v_pk_add_f32 v[94:95], v[94:95], v[98:99]
	v_pk_add_f32 v[96:97], v[96:97], v[100:101]
	v_pk_add_f32 v[100:101], v[90:91], v[102:103]
	v_cvt_pk_bf16_f32 v90, v94, v95
	v_mul_f32_e32 v95, v95, v95
	v_lshlrev_b32_e32 v104, 16, v145
	v_and_b32_e32 v105, 0xffff0000, v145
	v_fmac_f32_e32 v95, v94, v94
	v_mul_f32_e32 v94, v97, v97
	v_pk_add_f32 v[98:99], v[92:93], v[104:105]
	v_fmac_f32_e32 v94, v96, v96
	v_cvt_pk_bf16_f32 v91, v96, v97
	v_add_f32_e32 v94, v95, v94
	v_mul_f32_e32 v95, v101, v101
	v_mul_f32_e32 v96, v99, v99
	v_fmac_f32_e32 v95, v100, v100
	v_fmac_f32_e32 v96, v98, v98
	v_add_f32_e32 v95, v95, v96
	v_add_f32_e32 v102, v94, v95
	s_waitcnt vmcnt(6)
	v_lshlrev_b32_e32 v94, 16, v138
	v_and_b32_e32 v95, 0xffff0000, v138
	v_lshlrev_b32_e32 v96, 16, v139
	v_and_b32_e32 v97, 0xffff0000, v139
	v_cvt_pk_bf16_f32 v93, v98, v99
	v_lshlrev_b32_e32 v98, 16, v140
	v_and_b32_e32 v99, 0xffff0000, v140
	v_pk_add_f32 v[88:89], v[88:89], v[96:97]
	v_pk_add_f32 v[86:87], v[86:87], v[94:95]
	v_cvt_pk_bf16_f32 v92, v100, v101
	v_lshlrev_b32_e32 v100, 16, v141
	v_and_b32_e32 v101, 0xffff0000, v141
	v_pk_add_f32 v[96:97], v[82:83], v[98:99]
	v_mul_f32_e32 v82, v87, v87
	v_mul_f32_e32 v83, v89, v89
	v_pk_add_f32 v[94:95], v[84:85], v[100:101]
	v_fmac_f32_e32 v82, v86, v86
	v_fmac_f32_e32 v83, v88, v88
	v_add_f32_e32 v82, v82, v83
	v_mul_f32_e32 v83, v97, v97
	v_mul_f32_e32 v84, v95, v95
	v_fmac_f32_e32 v83, v96, v96
	v_fmac_f32_e32 v84, v94, v94
	v_add_f32_e32 v83, v83, v84
	v_add_f32_e32 v82, v82, v83
	v_add_f32_e32 v85, v102, v82
	ds_bpermute_b32 v100, v191, v85
	v_lshl_add_u64 v[82:83], s[36:37], 0, v[180:181]
	v_lshl_add_u64 v[98:99], v[168:169], 1, v[82:83]
	v_cvt_pk_bf16_f32 v84, v86, v87
	v_cvt_pk_bf16_f32 v86, v96, v97
	s_waitcnt lgkmcnt(0)
	v_add_f32_e32 v82, v85, v100
	ds_bpermute_b32 v83, v190, v82
	v_cvt_pk_bf16_f32 v85, v88, v89
	v_cvt_pk_bf16_f32 v87, v94, v95
	global_store_dwordx4 v[98:99], v[90:93], off
	global_store_dwordx4 v[98:99], v[84:87], off offset:256
	s_waitcnt lgkmcnt(0)
	v_add_f32_e32 v212, v82, v83
	s_waitcnt vmcnt(7)
	v_lshlrev_b32_e32 v82, 16, v134
	s_waitcnt lgkmcnt(0)
	v_and_b32_e32 v83, 0xffff0000, v134
	v_lshlrev_b32_e32 v84, 16, v135
	v_and_b32_e32 v85, 0xffff0000, v135
	v_lshlrev_b32_e32 v86, 16, v136
	v_and_b32_e32 v87, 0xffff0000, v136
	v_pk_add_f32 v[78:79], v[78:79], v[82:83]
	v_pk_add_f32 v[80:81], v[80:81], v[84:85]
	v_pk_add_f32 v[84:85], v[74:75], v[86:87]
	v_cvt_pk_bf16_f32 v74, v78, v79
	v_mul_f32_e32 v79, v79, v79
	v_lshlrev_b32_e32 v88, 16, v137
	v_and_b32_e32 v89, 0xffff0000, v137
	v_fmac_f32_e32 v79, v78, v78
	v_mul_f32_e32 v78, v81, v81
	v_pk_add_f32 v[82:83], v[76:77], v[88:89]
	v_fmac_f32_e32 v78, v80, v80
	v_cvt_pk_bf16_f32 v75, v80, v81
	v_add_f32_e32 v78, v79, v78
	v_mul_f32_e32 v79, v85, v85
	v_mul_f32_e32 v80, v83, v83
	v_fmac_f32_e32 v79, v84, v84
	v_fmac_f32_e32 v80, v82, v82
	v_add_f32_e32 v79, v79, v80
	v_add_f32_e32 v86, v78, v79
	s_waitcnt vmcnt(6)
	v_lshlrev_b32_e32 v78, 16, v130
	v_and_b32_e32 v79, 0xffff0000, v130
	v_lshlrev_b32_e32 v80, 16, v131
	v_and_b32_e32 v81, 0xffff0000, v131
	v_cvt_pk_bf16_f32 v77, v82, v83
	v_lshlrev_b32_e32 v82, 16, v132
	v_and_b32_e32 v83, 0xffff0000, v132
	v_pk_add_f32 v[72:73], v[72:73], v[80:81]
	v_pk_add_f32 v[70:71], v[70:71], v[78:79]
	v_cvt_pk_bf16_f32 v76, v84, v85
	v_lshlrev_b32_e32 v84, 16, v133
	v_and_b32_e32 v85, 0xffff0000, v133
	v_pk_add_f32 v[80:81], v[66:67], v[82:83]
	v_mul_f32_e32 v66, v71, v71
	v_mul_f32_e32 v67, v73, v73
	v_pk_add_f32 v[78:79], v[68:69], v[84:85]
	v_fmac_f32_e32 v66, v70, v70
	v_fmac_f32_e32 v67, v72, v72
	v_add_f32_e32 v66, v66, v67
	v_mul_f32_e32 v67, v81, v81
	v_mul_f32_e32 v68, v79, v79
	v_fmac_f32_e32 v67, v80, v80
	v_fmac_f32_e32 v68, v78, v78
	v_add_f32_e32 v67, v67, v68
	v_add_f32_e32 v66, v66, v67
	v_add_f32_e32 v69, v86, v66
	ds_bpermute_b32 v84, v191, v69
	v_lshl_add_u64 v[66:67], s[36:37], 0, v[176:177]
	v_lshl_add_u64 v[82:83], v[168:169], 1, v[66:67]
	v_cvt_pk_bf16_f32 v68, v70, v71
	v_cvt_pk_bf16_f32 v70, v80, v81
	s_waitcnt lgkmcnt(0)
	v_add_f32_e32 v66, v69, v84
	ds_bpermute_b32 v67, v190, v66
	v_cvt_pk_bf16_f32 v69, v72, v73
	v_cvt_pk_bf16_f32 v71, v78, v79
	global_store_dwordx4 v[82:83], v[74:77], off
	global_store_dwordx4 v[82:83], v[68:71], off offset:256
	s_waitcnt lgkmcnt(0)
	v_add_f32_e32 v213, v66, v67
	v_and_b32_e32 v214, 1, v187
	v_cmp_ne_u32_e64 s[60:61], 0, v214
	v_and_b32_e32 v214, 2, v187
	v_cmp_ne_u32_e64 s[100:101], 0, v214
	s_nop 1
	v_cndmask_b32_e64 v215, v210, v211, s[60:61]
	v_cndmask_b32_e64 v216, v212, v213, s[60:61]
	v_cndmask_b32_e64 v217, v215, v216, s[100:101]
	v_lshl_add_u32 v220, v187, 4, v172
	v_ashrrev_i32_e32 v221, 31, v220
	s_lshl_b32 s22, s46, 2
	v_lshlrev_b64 v[66:67], 6, v[220:221]
	s_ashr_i32 s23, s22, 31
	v_lshl_add_u64 v[66:67], s[84:85], 0, v[66:67]
	v_lshl_add_u64 v[66:67], s[22:23], 2, v[66:67]
	s_lshl_b32 s86, s74, 2
	v_lshl_add_u64 v[66:67], v[66:67], 0, s[86:87]
	global_store_dword v[66:67], v217, off
	v_add_u32_e32 v102, 0x80, v172
	v_ashrrev_i32_e32 v103, 31, v102
	v_lshlrev_b64 v[112:113], 11, v[102:103]
	s_waitcnt lgkmcnt(0)
; __device__ __forceinline__ float shx(float v, int lane, int o) { return __int_as_float(__builtin_amdgcn_ds_bpermute((lane ^ o) << 2, __float_as_int(v))); }
; __device__ __forceinline__ u32x4 pack8(const f32x4 a, const f32x4 b) { u32x4 w; w.x = cvt_pk_bf16(a[0], a[1]); w.y = cvt_pk_bf16(a[2], a[3]); w.z = cvt_pk_bf16(b[0], b[1]); w.w = cvt_pk_bf16(b[2], b[3]); return w; }
; __device__ __forceinline__ void unpack8(const u32x4 w, f32x4& a, f32x4& b) { a = (f32x4){bflo(w.x), bfhi(w.x), bflo(w.y), bfhi(w.y)}; b = (f32x4){bflo(w.z), bfhi(w.z), bflo(w.w), bfhi(w.w)}; }
;     __device__ __forceinline__ void operator()(const Acc& acc, const Unit& u, int wr, int wc, int fr, int fq) const {
;     ...
;         for (int ai = 0; ai < 2; ++ai) {
;             u32x4 hv[4][2];
; #pragma unroll
;             for (int m = 0; m < 4; ++m)
; #pragma unroll
;                 for (int bj = 0; bj < 2; ++bj) hv[m][bj] = *(const u32x4*)(hb + (size_t)(row0 + ai * 128 + m * 16) * DM + col0 + bj * 128);
; #pragma unroll
;             for (int m = 0; m < 4; ++m) { const size_t row = (size_t)(row0 + ai * 128 + m * 16); float sq = 0.f;
; #pragma unroll
;                 for (int bj = 0; bj < 2; ++bj) { f32x4 o0, o1; unpack8(hv[m][bj], o0, o1); o0 += acc[ai][bj][m][0] * sc; o1 += acc[ai][bj][m][1] * sc;
;                     *(u32x4*)(hb + row * DM + col0 + bj * 128) = pack8(o0, o1);
;                     sq += ((o0[0] * o0[0] + o0[1] * o0[1]) + (o0[2] * o0[2] + o0[3] * o0[3])) + ((o1[0] * o1[0] + o1[1] * o1[1]) + (o1[2] * o1[2] + o1[3] * o1[3])); }
;                 const int lane = fq * 16 + fr; sq += shx(sq, lane, 16); sq += shx(sq, lane, 32);
;                 if (fq == 0) ssq[row * 16 + u.pn * 4 + wc] = sq; } }
	v_lshl_add_u64 v[66:67], v[170:171], 0, v[112:113]
	global_load_dwordx4 v[104:107], v[66:67], off
	global_load_dwordx4 v[108:111], v[66:67], off offset:256
	v_add_u32_e32 v98, 0x90, v172
	v_ashrrev_i32_e32 v99, 31, v98
	v_add_u32_e32 v94, 0xa0, v172
	v_lshlrev_b64 v[100:101], 11, v[98:99]
	v_ashrrev_i32_e32 v95, 31, v94
	v_add_u32_e32 v90, 0xb0, v172
	v_lshl_add_u64 v[66:67], v[170:171], 0, v[100:101]
	v_lshlrev_b64 v[96:97], 11, v[94:95]
	v_ashrrev_i32_e32 v91, 31, v90
	global_load_dwordx4 v[86:89], v[66:67], off
	global_load_dwordx4 v[82:85], v[66:67], off offset:256
	v_lshl_add_u64 v[66:67], v[170:171], 0, v[96:97]
	v_lshlrev_b64 v[92:93], 11, v[90:91]
	global_load_dwordx4 v[78:81], v[66:67], off
	global_load_dwordx4 v[74:77], v[66:67], off offset:256
	v_lshl_add_u64 v[66:67], v[170:171], 0, v[92:93]
	global_load_dwordx4 v[70:73], v[66:67], off
	s_nop 0
	global_load_dwordx4 v[66:69], v[66:67], off offset:256
	v_lshl_add_u64 v[112:113], s[36:37], 0, v[112:113]
	v_lshl_add_u64 v[112:113], v[168:169], 1, v[112:113]
	s_waitcnt vmcnt(7)
	v_lshlrev_b32_e32 v114, 16, v104
	v_and_b32_e32 v115, 0xffff0000, v104
	v_lshlrev_b32_e32 v104, 16, v105
	v_and_b32_e32 v105, 0xffff0000, v105
	v_lshlrev_b32_e32 v116, 16, v106
	v_and_b32_e32 v117, 0xffff0000, v106
	v_lshlrev_b32_e32 v106, 16, v107
	v_and_b32_e32 v107, 0xffff0000, v107
	v_pk_add_f32 v[64:65], v[64:65], v[104:105]
	v_pk_add_f32 v[62:63], v[62:63], v[114:115]
	v_pk_add_f32 v[104:105], v[60:61], v[106:107]
	v_pk_add_f32 v[106:107], v[58:59], v[116:117]
	v_cvt_pk_bf16_f32 v58, v62, v63
	v_cvt_pk_bf16_f32 v59, v64, v65
	v_cvt_pk_bf16_f32 v60, v106, v107
	v_cvt_pk_bf16_f32 v61, v104, v105
	global_store_dwordx4 v[112:113], v[58:61], off
	s_nop 1
	v_mul_f32_e32 v58, v63, v63
	v_mul_f32_e32 v59, v65, v65
	v_fmac_f32_e32 v58, v62, v62
	v_fmac_f32_e32 v59, v64, v64
	v_add_f32_e32 v58, v58, v59
	v_mul_f32_e32 v59, v107, v107
	v_mul_f32_e32 v60, v105, v105
	v_fmac_f32_e32 v59, v106, v106
	v_fmac_f32_e32 v60, v104, v104
	v_add_f32_e32 v59, v59, v60
	v_add_f32_e32 v104, v58, v59
	s_waitcnt vmcnt(7)
	v_lshlrev_b32_e32 v58, 16, v108
	v_and_b32_e32 v59, 0xffff0000, v108
	v_lshlrev_b32_e32 v60, 16, v109
	v_and_b32_e32 v61, 0xffff0000, v109
	v_lshlrev_b32_e32 v62, 16, v110
	v_and_b32_e32 v63, 0xffff0000, v110
	v_lshlrev_b32_e32 v64, 16, v111
	v_and_b32_e32 v65, 0xffff0000, v111
	v_pk_add_f32 v[56:57], v[56:57], v[60:61]
	v_pk_add_f32 v[54:55], v[54:55], v[58:59]
	v_pk_add_f32 v[58:59], v[52:53], v[64:65]
	v_pk_add_f32 v[60:61], v[50:51], v[62:63]
	v_cvt_pk_bf16_f32 v50, v54, v55
	v_cvt_pk_bf16_f32 v51, v56, v57
	v_cvt_pk_bf16_f32 v52, v60, v61
	v_cvt_pk_bf16_f32 v53, v58, v59
	global_store_dwordx4 v[112:113], v[50:53], off offset:256
	s_nop 1
	v_mul_f32_e32 v50, v55, v55
	v_mul_f32_e32 v51, v57, v57
	v_fmac_f32_e32 v50, v54, v54
	v_fmac_f32_e32 v51, v56, v56
	v_add_f32_e32 v50, v50, v51
	v_mul_f32_e32 v51, v61, v61
	v_mul_f32_e32 v52, v59, v59
	v_fmac_f32_e32 v51, v60, v60
	v_fmac_f32_e32 v52, v58, v58
	v_add_f32_e32 v51, v51, v52
	v_add_f32_e32 v50, v50, v51
	v_add_f32_e32 v50, v104, v50
	ds_bpermute_b32 v51, v191, v50
	s_waitcnt lgkmcnt(0)
	v_add_f32_e32 v50, v50, v51
	ds_bpermute_b32 v51, v190, v50
	s_waitcnt lgkmcnt(0)
	v_add_f32_e32 v210, v50, v51
	s_waitcnt vmcnt(7)
	v_lshlrev_b32_e32 v50, 16, v86
	s_waitcnt lgkmcnt(0)
	v_and_b32_e32 v51, 0xffff0000, v86
	v_lshlrev_b32_e32 v52, 16, v87
	v_and_b32_e32 v53, 0xffff0000, v87
	v_lshlrev_b32_e32 v54, 16, v88
	v_and_b32_e32 v55, 0xffff0000, v88
	v_pk_add_f32 v[46:47], v[46:47], v[50:51]
	v_pk_add_f32 v[48:49], v[48:49], v[52:53]
	v_pk_add_f32 v[52:53], v[42:43], v[54:55]
	v_cvt_pk_bf16_f32 v42, v46, v47
	v_mul_f32_e32 v47, v47, v47
	v_lshlrev_b32_e32 v56, 16, v89
	v_and_b32_e32 v57, 0xffff0000, v89
	v_fmac_f32_e32 v47, v46, v46
	v_mul_f32_e32 v46, v49, v49
	v_pk_add_f32 v[50:51], v[44:45], v[56:57]
	v_fmac_f32_e32 v46, v48, v48
	v_cvt_pk_bf16_f32 v43, v48, v49
	v_add_f32_e32 v46, v47, v46
	v_mul_f32_e32 v47, v53, v53
	v_mul_f32_e32 v48, v51, v51
	v_fmac_f32_e32 v47, v52, v52
	v_fmac_f32_e32 v48, v50, v50
	v_add_f32_e32 v47, v47, v48
	v_add_f32_e32 v54, v46, v47
	s_waitcnt vmcnt(6)
	v_lshlrev_b32_e32 v46, 16, v82
	v_and_b32_e32 v47, 0xffff0000, v82
	v_lshlrev_b32_e32 v48, 16, v83
	v_and_b32_e32 v49, 0xffff0000, v83
	v_cvt_pk_bf16_f32 v45, v50, v51
	v_lshlrev_b32_e32 v50, 16, v84
	v_and_b32_e32 v51, 0xffff0000, v84
	v_pk_add_f32 v[40:41], v[40:41], v[48:49]
	v_pk_add_f32 v[38:39], v[38:39], v[46:47]
	v_cvt_pk_bf16_f32 v44, v52, v53
	v_lshlrev_b32_e32 v52, 16, v85
	v_and_b32_e32 v53, 0xffff0000, v85
	v_pk_add_f32 v[48:49], v[34:35], v[50:51]
	v_mul_f32_e32 v34, v39, v39
	v_mul_f32_e32 v35, v41, v41
	v_pk_add_f32 v[46:47], v[36:37], v[52:53]
	v_fmac_f32_e32 v34, v38, v38
	v_fmac_f32_e32 v35, v40, v40
	v_add_f32_e32 v34, v34, v35
	v_mul_f32_e32 v35, v49, v49
	v_mul_f32_e32 v36, v47, v47
	v_fmac_f32_e32 v35, v48, v48
	v_fmac_f32_e32 v36, v46, v46
	v_add_f32_e32 v35, v35, v36
	v_add_f32_e32 v34, v34, v35
	v_add_f32_e32 v37, v54, v34
	ds_bpermute_b32 v52, v191, v37
	v_lshl_add_u64 v[34:35], s[36:37], 0, v[100:101]
	v_lshl_add_u64 v[50:51], v[168:169], 1, v[34:35]
	v_cvt_pk_bf16_f32 v36, v38, v39
	v_cvt_pk_bf16_f32 v38, v48, v49
	s_waitcnt lgkmcnt(0)
; __device__ __forceinline__ float shx(float v, int lane, int o) { return __int_as_float(__builtin_amdgcn_ds_bpermute((lane ^ o) << 2, __float_as_int(v))); }
; __device__ __forceinline__ u32x4 pack8(const f32x4 a, const f32x4 b) { u32x4 w; w.x = cvt_pk_bf16(a[0], a[1]); w.y = cvt_pk_bf16(a[2], a[3]); w.z = cvt_pk_bf16(b[0], b[1]); w.w = cvt_pk_bf16(b[2], b[3]); return w; }
; __device__ __forceinline__ void unpack8(const u32x4 w, f32x4& a, f32x4& b) { a = (f32x4){bflo(w.x), bfhi(w.x), bflo(w.y), bfhi(w.y)}; b = (f32x4){bflo(w.z), bfhi(w.z), bflo(w.w), bfhi(w.w)}; }
;     __device__ __forceinline__ void operator()(const Acc& acc, const Unit& u, int wr, int wc, int fr, int fq) const {
;     ...
;         for (int ai = 0; ai < 2; ++ai) {
;             u32x4 hv[4][2];
; #pragma unroll
;             for (int m = 0; m < 4; ++m)
; #pragma unroll
;                 for (int bj = 0; bj < 2; ++bj) hv[m][bj] = *(const u32x4*)(hb + (size_t)(row0 + ai * 128 + m * 16) * DM + col0 + bj * 128);
; #pragma unroll
;             for (int m = 0; m < 4; ++m) { const size_t row = (size_t)(row0 + ai * 128 + m * 16); float sq = 0.f;
; #pragma unroll
;                 for (int bj = 0; bj < 2; ++bj) { f32x4 o0, o1; unpack8(hv[m][bj], o0, o1); o0 += acc[ai][bj][m][0] * sc; o1 += acc[ai][bj][m][1] * sc;
;                     *(u32x4*)(hb + row * DM + col0 + bj * 128) = pack8(o0, o1);
;                     sq += ((o0[0] * o0[0] + o0[1] * o0[1]) + (o0[2] * o0[2] + o0[3] * o0[3])) + ((o1[0] * o1[0] + o1[1] * o1[1]) + (o1[2] * o1[2] + o1[3] * o1[3])); }
;                 const int lane = fq * 16 + fr; sq += shx(sq, lane, 16); sq += shx(sq, lane, 32);
;                 if (fq == 0) ssq[row * 16 + u.pn * 4 + wc] = sq; } }
	v_add_f32_e32 v34, v37, v52
	ds_bpermute_b32 v35, v190, v34
	v_cvt_pk_bf16_f32 v37, v40, v41
	v_cvt_pk_bf16_f32 v39, v46, v47
	global_store_dwordx4 v[50:51], v[42:45], off
	global_store_dwordx4 v[50:51], v[36:39], off offset:256
	s_waitcnt lgkmcnt(0)
	v_add_f32_e32 v211, v34, v35
	s_waitcnt vmcnt(7)
	v_lshlrev_b32_e32 v34, 16, v78
	s_waitcnt lgkmcnt(0)
	v_and_b32_e32 v35, 0xffff0000, v78
	v_lshlrev_b32_e32 v36, 16, v79
	v_and_b32_e32 v37, 0xffff0000, v79
	v_lshlrev_b32_e32 v38, 16, v80
	v_and_b32_e32 v39, 0xffff0000, v80
	v_pk_add_f32 v[30:31], v[30:31], v[34:35]
	v_pk_add_f32 v[32:33], v[32:33], v[36:37]
	v_pk_add_f32 v[36:37], v[26:27], v[38:39]
	v_cvt_pk_bf16_f32 v26, v30, v31
	v_mul_f32_e32 v31, v31, v31
	v_lshlrev_b32_e32 v40, 16, v81
	v_and_b32_e32 v41, 0xffff0000, v81
	v_fmac_f32_e32 v31, v30, v30
	v_mul_f32_e32 v30, v33, v33
	v_pk_add_f32 v[34:35], v[28:29], v[40:41]
	v_fmac_f32_e32 v30, v32, v32
	v_cvt_pk_bf16_f32 v27, v32, v33
	v_add_f32_e32 v30, v31, v30
	v_mul_f32_e32 v31, v37, v37
	v_mul_f32_e32 v32, v35, v35
	v_fmac_f32_e32 v31, v36, v36
	v_fmac_f32_e32 v32, v34, v34
	v_add_f32_e32 v31, v31, v32
	v_add_f32_e32 v38, v30, v31
	s_waitcnt vmcnt(6)
	v_lshlrev_b32_e32 v30, 16, v74
	v_and_b32_e32 v31, 0xffff0000, v74
	v_lshlrev_b32_e32 v32, 16, v75
	v_and_b32_e32 v33, 0xffff0000, v75
	v_cvt_pk_bf16_f32 v29, v34, v35
	v_lshlrev_b32_e32 v34, 16, v76
	v_and_b32_e32 v35, 0xffff0000, v76
	v_pk_add_f32 v[24:25], v[24:25], v[32:33]
	v_pk_add_f32 v[22:23], v[22:23], v[30:31]
	v_cvt_pk_bf16_f32 v28, v36, v37
	v_lshlrev_b32_e32 v36, 16, v77
	v_and_b32_e32 v37, 0xffff0000, v77
	v_pk_add_f32 v[32:33], v[18:19], v[34:35]
	v_mul_f32_e32 v18, v23, v23
	v_mul_f32_e32 v19, v25, v25
	v_pk_add_f32 v[30:31], v[20:21], v[36:37]
	v_fmac_f32_e32 v18, v22, v22
	v_fmac_f32_e32 v19, v24, v24
	v_add_f32_e32 v18, v18, v19
	v_mul_f32_e32 v19, v33, v33
	v_mul_f32_e32 v20, v31, v31
	v_fmac_f32_e32 v19, v32, v32
	v_fmac_f32_e32 v20, v30, v30
	v_add_f32_e32 v19, v19, v20
	v_add_f32_e32 v18, v18, v19
	v_add_f32_e32 v21, v38, v18
	ds_bpermute_b32 v36, v191, v21
	v_lshl_add_u64 v[18:19], s[36:37], 0, v[96:97]
	v_lshl_add_u64 v[34:35], v[168:169], 1, v[18:19]
	v_cvt_pk_bf16_f32 v20, v22, v23
	v_cvt_pk_bf16_f32 v22, v32, v33
	s_waitcnt lgkmcnt(0)
	v_add_f32_e32 v18, v21, v36
	ds_bpermute_b32 v19, v190, v18
	v_cvt_pk_bf16_f32 v21, v24, v25
	v_cvt_pk_bf16_f32 v23, v30, v31
	global_store_dwordx4 v[34:35], v[26:29], off
	global_store_dwordx4 v[34:35], v[20:23], off offset:256
	s_waitcnt lgkmcnt(0)
	v_add_f32_e32 v212, v18, v19
	s_waitcnt vmcnt(7)
	v_lshlrev_b32_e32 v18, 16, v70
	s_waitcnt lgkmcnt(0)
	v_and_b32_e32 v19, 0xffff0000, v70
	v_lshlrev_b32_e32 v20, 16, v71
	v_and_b32_e32 v21, 0xffff0000, v71
	v_lshlrev_b32_e32 v22, 16, v72
	v_and_b32_e32 v23, 0xffff0000, v72
	v_pk_add_f32 v[14:15], v[14:15], v[18:19]
	v_pk_add_f32 v[16:17], v[16:17], v[20:21]
	v_pk_add_f32 v[20:21], v[10:11], v[22:23]
	v_cvt_pk_bf16_f32 v10, v14, v15
	v_mul_f32_e32 v15, v15, v15
	v_lshlrev_b32_e32 v24, 16, v73
	v_and_b32_e32 v25, 0xffff0000, v73
	v_fmac_f32_e32 v15, v14, v14
	v_mul_f32_e32 v14, v17, v17
	v_pk_add_f32 v[18:19], v[12:13], v[24:25]
	v_fmac_f32_e32 v14, v16, v16
	v_cvt_pk_bf16_f32 v11, v16, v17
	v_add_f32_e32 v14, v15, v14
	v_mul_f32_e32 v15, v21, v21
	v_mul_f32_e32 v16, v19, v19
	v_fmac_f32_e32 v15, v20, v20
	v_fmac_f32_e32 v16, v18, v18
	v_add_f32_e32 v15, v15, v16
	v_add_f32_e32 v22, v14, v15
	s_waitcnt vmcnt(6)
	v_lshlrev_b32_e32 v14, 16, v66
	v_and_b32_e32 v15, 0xffff0000, v66
	v_lshlrev_b32_e32 v16, 16, v67
	v_and_b32_e32 v17, 0xffff0000, v67
	v_cvt_pk_bf16_f32 v13, v18, v19
	v_lshlrev_b32_e32 v18, 16, v68
	v_and_b32_e32 v19, 0xffff0000, v68
	v_pk_add_f32 v[8:9], v[8:9], v[16:17]
	v_pk_add_f32 v[6:7], v[6:7], v[14:15]
	v_cvt_pk_bf16_f32 v12, v20, v21
	v_lshlrev_b32_e32 v20, 16, v69
	v_and_b32_e32 v21, 0xffff0000, v69
	v_pk_add_f32 v[16:17], v[2:3], v[18:19]
	v_mul_f32_e32 v2, v7, v7
	v_mul_f32_e32 v3, v9, v9
	v_pk_add_f32 v[14:15], v[4:5], v[20:21]
	v_fmac_f32_e32 v2, v6, v6
	v_fmac_f32_e32 v3, v8, v8
	v_add_f32_e32 v2, v2, v3
	v_mul_f32_e32 v3, v17, v17
	v_mul_f32_e32 v4, v15, v15
	v_fmac_f32_e32 v3, v16, v16
	v_fmac_f32_e32 v4, v14, v14
	v_add_f32_e32 v3, v3, v4
	v_add_f32_e32 v2, v2, v3
	v_add_f32_e32 v5, v22, v2
	ds_bpermute_b32 v20, v191, v5
	v_lshl_add_u64 v[2:3], s[36:37], 0, v[92:93]
	v_lshl_add_u64 v[18:19], v[168:169], 1, v[2:3]
	v_cvt_pk_bf16_f32 v4, v6, v7
	v_cvt_pk_bf16_f32 v6, v16, v17
	s_waitcnt lgkmcnt(0)
	v_add_f32_e32 v2, v5, v20
	ds_bpermute_b32 v3, v190, v2
	v_cvt_pk_bf16_f32 v5, v8, v9
	v_cvt_pk_bf16_f32 v7, v14, v15
	global_store_dwordx4 v[18:19], v[10:13], off
	global_store_dwordx4 v[18:19], v[4:7], off offset:256
	s_waitcnt lgkmcnt(0)
	v_add_f32_e32 v213, v2, v3
	v_and_b32_e32 v214, 1, v187
	v_cmp_ne_u32_e64 s[60:61], 0, v214
	v_and_b32_e32 v214, 2, v187
	v_cmp_ne_u32_e64 s[100:101], 0, v214
	s_nop 1
	v_cndmask_b32_e64 v215, v210, v211, s[60:61]
	v_cndmask_b32_e64 v216, v212, v213, s[60:61]
	v_cndmask_b32_e64 v217, v215, v216, s[100:101]
	v_lshl_add_u32 v220, v187, 4, v172
	v_add_u32_e32 v220, 0x80, v220
	v_ashrrev_i32_e32 v221, 31, v220
	s_lshl_b32 s22, s46, 2
	v_lshlrev_b64 v[2:3], 6, v[220:221]
	s_ashr_i32 s23, s22, 31
	v_lshl_add_u64 v[2:3], s[84:85], 0, v[2:3]
	v_lshl_add_u64 v[2:3], s[22:23], 2, v[2:3]
	s_lshl_b32 s86, s74, 2
	v_lshl_add_u64 v[2:3], v[2:3], 0, s[86:87]
	global_store_dword v[2:3], v217, off
	s_branch .LBB0_47

; __device__ __forceinline__ float shx(float v, int lane, int o) { return __int_as_float(__builtin_amdgcn_ds_bpermute((lane ^ o) << 2, __float_as_int(v))); }
; __device__ __forceinline__ u32x4 pack8(const f32x4 a, const f32x4 b) { u32x4 w; w.x = cvt_pk_bf16(a[0], a[1]); w.y = cvt_pk_bf16(a[2], a[3]); w.z = cvt_pk_bf16(b[0], b[1]); w.w = cvt_pk_bf16(b[2], b[3]); return w; }
; __device__ __forceinline__ void unpack8(const u32x4 w, f32x4& a, f32x4& b) { a = (f32x4){bflo(w.x), bfhi(w.x), bflo(w.y), bfhi(w.y)}; b = (f32x4){bflo(w.z), bfhi(w.z), bflo(w.w), bfhi(w.w)}; }
;     __device__ __forceinline__ void operator()(const Acc& acc, const Unit& u, int wr, int wc, int fr, int fq) const {
;     ...
;         for (int ai = 0; ai < 2; ++ai) {
;             u32x4 hv[4][2];
; #pragma unroll
;             for (int m = 0; m < 4; ++m)
; #pragma unroll
;                 for (int bj = 0; bj < 2; ++bj) hv[m][bj] = *(const u32x4*)(hb + (size_t)(row0 + ai * 128 + m * 16) * DM + col0 + bj * 128);
; #pragma unroll
;             for (int m = 0; m < 4; ++m) { const size_t row = (size_t)(row0 + ai * 128 + m * 16); float sq = 0.f;
; #pragma unroll
;                 for (int bj = 0; bj < 2; ++bj) { f32x4 o0, o1; unpack8(hv[m][bj], o0, o1); o0 += acc[ai][bj][m][0] * sc; o1 += acc[ai][bj][m][1] * sc;
;                     *(u32x4*)(hb + row * DM + col0 + bj * 128) = pack8(o0, o1);
;                     sq += ((o0[0] * o0[0] + o0[1] * o0[1]) + (o0[2] * o0[2] + o0[3] * o0[3])) + ((o1[0] * o1[0] + o1[1] * o1[1]) + (o1[2] * o1[2] + o1[3] * o1[3])); }
;                 const int lane = fq * 16 + fr; sq += shx(sq, lane, 16); sq += shx(sq, lane, 32);
;                 if (fq == 0) ssq[row * 16 + u.pn * 4 + wc] = sq; } }
.LBB0_213:
	v_readlane_b32 s92, v253, 42
	s_andn2_b64 vcc, exec, s[66:67]
	s_cbranch_vccnz .LBB0_197
	v_lshl_add_u32 v172, s64, 8, v130
	v_lshlrev_b32_e32 v130, 2, v133
	v_lshlrev_b64 v[202:203], 1, v[168:169]
	v_ashrrev_i32_e32 v173, 31, v172
	v_lshl_add_u32 v130, v132, 6, v130
	v_lshl_add_u64 v[170:171], s[36:37], 0, v[202:203]
	v_lshlrev_b64 v[204:205], 11, v[172:173]
	v_xor_b32_e32 v191, 64, v130
	v_xor_b32_e32 v190, 0x80, v130
	v_lshl_add_u64 v[130:131], v[170:171], 0, v[204:205]
	global_load_dwordx4 v[192:195], v[130:131], off
	global_load_dwordx4 v[154:157], v[130:131], off offset:256
	v_add_u32_e32 v182, 16, v172
	v_ashrrev_i32_e32 v183, 31, v182
	v_add_u32_e32 v178, 32, v172
	v_lshlrev_b64 v[184:185], 11, v[182:183]
	v_ashrrev_i32_e32 v179, 31, v178
	v_add_u32_e32 v174, 48, v172
	v_lshl_add_u64 v[130:131], v[170:171], 0, v[184:185]
	v_lshlrev_b64 v[180:181], 11, v[178:179]
	v_ashrrev_i32_e32 v175, 31, v174
	global_load_dwordx4 v[150:153], v[130:131], off
	global_load_dwordx4 v[146:149], v[130:131], off offset:256
	v_lshl_add_u64 v[130:131], v[170:171], 0, v[180:181]
	v_lshlrev_b64 v[176:177], 11, v[174:175]
	global_load_dwordx4 v[142:145], v[130:131], off
	global_load_dwordx4 v[138:141], v[130:131], off offset:256
	v_lshl_add_u64 v[130:131], v[170:171], 0, v[176:177]
	v_cmp_eq_u32_e32 vcc, 0, v132
	global_load_dwordx4 v[134:137], v[130:131], off
	s_nop 0
	global_load_dwordx4 v[130:133], v[130:131], off offset:256
	v_lshl_add_u64 v[204:205], s[36:37], 0, v[204:205]
	v_lshl_add_u64 v[202:203], v[204:205], 0, v[202:203]
	s_waitcnt vmcnt(7)
	v_lshlrev_b32_e32 v206, 16, v192
	v_and_b32_e32 v207, 0xffff0000, v192
	v_lshlrev_b32_e32 v192, 16, v193
	v_and_b32_e32 v193, 0xffff0000, v193
	v_lshlrev_b32_e32 v208, 16, v194
	v_and_b32_e32 v209, 0xffff0000, v194
	v_lshlrev_b32_e32 v194, 16, v195
	v_and_b32_e32 v195, 0xffff0000, v195
	v_pk_add_f32 v[128:129], v[128:129], v[192:193]
	v_pk_add_f32 v[126:127], v[126:127], v[206:207]
	v_pk_add_f32 v[192:193], v[124:125], v[194:195]
	v_pk_add_f32 v[194:195], v[122:123], v[208:209]
	v_cvt_pk_bf16_f32 v122, v126, v127
	v_cvt_pk_bf16_f32 v123, v128, v129
	v_cvt_pk_bf16_f32 v124, v194, v195
	v_cvt_pk_bf16_f32 v125, v192, v193
	global_store_dwordx4 v[202:203], v[122:125], off
	s_nop 1
	v_mul_f32_e32 v122, v127, v127
	v_mul_f32_e32 v123, v129, v129
	v_fmac_f32_e32 v122, v126, v126
	v_fmac_f32_e32 v123, v128, v128
	v_add_f32_e32 v122, v122, v123
	v_mul_f32_e32 v123, v195, v195
	v_mul_f32_e32 v124, v193, v193
	v_fmac_f32_e32 v123, v194, v194
	v_fmac_f32_e32 v124, v192, v192
	v_add_f32_e32 v123, v123, v124
	v_add_f32_e32 v192, v122, v123
	s_waitcnt vmcnt(7)
	v_lshlrev_b32_e32 v122, 16, v154
	v_and_b32_e32 v123, 0xffff0000, v154
	v_lshlrev_b32_e32 v124, 16, v155
	v_and_b32_e32 v125, 0xffff0000, v155
	v_lshlrev_b32_e32 v126, 16, v156
	v_and_b32_e32 v127, 0xffff0000, v156
	v_lshlrev_b32_e32 v128, 16, v157
	v_and_b32_e32 v129, 0xffff0000, v157
	v_pk_add_f32 v[120:121], v[120:121], v[124:125]
	v_pk_add_f32 v[118:119], v[118:119], v[122:123]
	v_pk_add_f32 v[122:123], v[116:117], v[128:129]
	v_pk_add_f32 v[124:125], v[114:115], v[126:127]
	v_cvt_pk_bf16_f32 v114, v118, v119
	v_cvt_pk_bf16_f32 v115, v120, v121
	v_cvt_pk_bf16_f32 v116, v124, v125
	v_cvt_pk_bf16_f32 v117, v122, v123
	global_store_dwordx4 v[202:203], v[114:117], off offset:256
	s_nop 1
	v_mul_f32_e32 v114, v119, v119
	v_mul_f32_e32 v115, v121, v121
	v_fmac_f32_e32 v114, v118, v118
	v_fmac_f32_e32 v115, v120, v120
	v_add_f32_e32 v114, v114, v115
	v_mul_f32_e32 v115, v125, v125
	v_mul_f32_e32 v116, v123, v123
	v_fmac_f32_e32 v115, v124, v124
	v_fmac_f32_e32 v116, v122, v122
	v_add_f32_e32 v115, v115, v116
	v_add_f32_e32 v114, v114, v115
	v_add_f32_e32 v114, v192, v114
	ds_bpermute_b32 v115, v191, v114
	s_waitcnt lgkmcnt(0)
	v_add_f32_e32 v114, v114, v115
	ds_bpermute_b32 v115, v190, v114
	s_waitcnt lgkmcnt(0)
	v_add_f32_e32 v210, v114, v115
	s_waitcnt vmcnt(7)
	v_lshlrev_b32_e32 v114, 16, v150
	s_waitcnt lgkmcnt(0)
	v_and_b32_e32 v115, 0xffff0000, v150
	v_lshlrev_b32_e32 v116, 16, v151
	v_and_b32_e32 v117, 0xffff0000, v151
	v_lshlrev_b32_e32 v118, 16, v152
	v_and_b32_e32 v119, 0xffff0000, v152
	v_pk_add_f32 v[110:111], v[110:111], v[114:115]
	v_pk_add_f32 v[112:113], v[112:113], v[116:117]
	v_pk_add_f32 v[116:117], v[106:107], v[118:119]
	v_cvt_pk_bf16_f32 v106, v110, v111
	v_mul_f32_e32 v111, v111, v111
	v_lshlrev_b32_e32 v120, 16, v153
	v_and_b32_e32 v121, 0xffff0000, v153
	v_fmac_f32_e32 v111, v110, v110
	v_mul_f32_e32 v110, v113, v113
	v_pk_add_f32 v[114:115], v[108:109], v[120:121]
	v_fmac_f32_e32 v110, v112, v112
	v_cvt_pk_bf16_f32 v107, v112, v113
	v_add_f32_e32 v110, v111, v110
	v_mul_f32_e32 v111, v117, v117
	v_mul_f32_e32 v112, v115, v115
	v_fmac_f32_e32 v111, v116, v116
	v_fmac_f32_e32 v112, v114, v114
	v_add_f32_e32 v111, v111, v112
	v_add_f32_e32 v118, v110, v111
	s_waitcnt vmcnt(6)
	v_lshlrev_b32_e32 v110, 16, v146
	v_and_b32_e32 v111, 0xffff0000, v146
	v_lshlrev_b32_e32 v112, 16, v147
	v_and_b32_e32 v113, 0xffff0000, v147
	v_cvt_pk_bf16_f32 v109, v114, v115
	v_lshlrev_b32_e32 v114, 16, v148
	v_and_b32_e32 v115, 0xffff0000, v148
	v_pk_add_f32 v[104:105], v[104:105], v[112:113]
	v_pk_add_f32 v[102:103], v[102:103], v[110:111]
	v_cvt_pk_bf16_f32 v108, v116, v117
	v_lshlrev_b32_e32 v116, 16, v149
	v_and_b32_e32 v117, 0xffff0000, v149
	v_pk_add_f32 v[112:113], v[98:99], v[114:115]
	v_mul_f32_e32 v98, v103, v103
	v_mul_f32_e32 v99, v105, v105
	v_pk_add_f32 v[110:111], v[100:101], v[116:117]
	v_fmac_f32_e32 v98, v102, v102
	v_fmac_f32_e32 v99, v104, v104
	v_add_f32_e32 v98, v98, v99
	v_mul_f32_e32 v99, v113, v113
	v_mul_f32_e32 v100, v111, v111
	v_fmac_f32_e32 v99, v112, v112
	v_fmac_f32_e32 v100, v110, v110
	v_add_f32_e32 v99, v99, v100
	v_add_f32_e32 v98, v98, v99
	v_add_f32_e32 v101, v118, v98
	ds_bpermute_b32 v116, v191, v101
	v_lshl_add_u64 v[98:99], s[36:37], 0, v[184:185]
	v_lshl_add_u64 v[114:115], v[168:169], 1, v[98:99]
	v_cvt_pk_bf16_f32 v100, v102, v103
	v_cvt_pk_bf16_f32 v102, v112, v113
	s_waitcnt lgkmcnt(0)
; __device__ __forceinline__ float shx(float v, int lane, int o) { return __int_as_float(__builtin_amdgcn_ds_bpermute((lane ^ o) << 2, __float_as_int(v))); }
; __device__ __forceinline__ u32x4 pack8(const f32x4 a, const f32x4 b) { u32x4 w; w.x = cvt_pk_bf16(a[0], a[1]); w.y = cvt_pk_bf16(a[2], a[3]); w.z = cvt_pk_bf16(b[0], b[1]); w.w = cvt_pk_bf16(b[2], b[3]); return w; }
; __device__ __forceinline__ void unpack8(const u32x4 w, f32x4& a, f32x4& b) { a = (f32x4){bflo(w.x), bfhi(w.x), bflo(w.y), bfhi(w.y)}; b = (f32x4){bflo(w.z), bfhi(w.z), bflo(w.w), bfhi(w.w)}; }
;     __device__ __forceinline__ void operator()(const Acc& acc, const Unit& u, int wr, int wc, int fr, int fq) const {
;     ...
;         for (int ai = 0; ai < 2; ++ai) {
;             u32x4 hv[4][2];
; #pragma unroll
;             for (int m = 0; m < 4; ++m)
; #pragma unroll
;                 for (int bj = 0; bj < 2; ++bj) hv[m][bj] = *(const u32x4*)(hb + (size_t)(row0 + ai * 128 + m * 16) * DM + col0 + bj * 128);
; #pragma unroll
;             for (int m = 0; m < 4; ++m) { const size_t row = (size_t)(row0 + ai * 128 + m * 16); float sq = 0.f;
; #pragma unroll
;                 for (int bj = 0; bj < 2; ++bj) { f32x4 o0, o1; unpack8(hv[m][bj], o0, o1); o0 += acc[ai][bj][m][0] * sc; o1 += acc[ai][bj][m][1] * sc;
;                     *(u32x4*)(hb + row * DM + col0 + bj * 128) = pack8(o0, o1);
;                     sq += ((o0[0] * o0[0] + o0[1] * o0[1]) + (o0[2] * o0[2] + o0[3] * o0[3])) + ((o1[0] * o1[0] + o1[1] * o1[1]) + (o1[2] * o1[2] + o1[3] * o1[3])); }
;                 const int lane = fq * 16 + fr; sq += shx(sq, lane, 16); sq += shx(sq, lane, 32);
;                 if (fq == 0) ssq[row * 16 + u.pn * 4 + wc] = sq; } }
	v_add_f32_e32 v98, v101, v116
	ds_bpermute_b32 v99, v190, v98
	v_cvt_pk_bf16_f32 v101, v104, v105
	v_cvt_pk_bf16_f32 v103, v110, v111
	global_store_dwordx4 v[114:115], v[106:109], off
	global_store_dwordx4 v[114:115], v[100:103], off offset:256
	s_waitcnt lgkmcnt(0)
	v_add_f32_e32 v211, v98, v99
	s_waitcnt vmcnt(7)
	v_lshlrev_b32_e32 v98, 16, v142
	s_waitcnt lgkmcnt(0)
	v_and_b32_e32 v99, 0xffff0000, v142
	v_lshlrev_b32_e32 v100, 16, v143
	v_and_b32_e32 v101, 0xffff0000, v143
	v_lshlrev_b32_e32 v102, 16, v144
	v_and_b32_e32 v103, 0xffff0000, v144
	v_pk_add_f32 v[94:95], v[94:95], v[98:99]
	v_pk_add_f32 v[96:97], v[96:97], v[100:101]
	v_pk_add_f32 v[100:101], v[90:91], v[102:103]
	v_cvt_pk_bf16_f32 v90, v94, v95
	v_mul_f32_e32 v95, v95, v95
	v_lshlrev_b32_e32 v104, 16, v145
	v_and_b32_e32 v105, 0xffff0000, v145
	v_fmac_f32_e32 v95, v94, v94
	v_mul_f32_e32 v94, v97, v97
	v_pk_add_f32 v[98:99], v[92:93], v[104:105]
	v_fmac_f32_e32 v94, v96, v96
	v_cvt_pk_bf16_f32 v91, v96, v97
	v_add_f32_e32 v94, v95, v94
	v_mul_f32_e32 v95, v101, v101
	v_mul_f32_e32 v96, v99, v99
	v_fmac_f32_e32 v95, v100, v100
	v_fmac_f32_e32 v96, v98, v98
	v_add_f32_e32 v95, v95, v96
	v_add_f32_e32 v102, v94, v95
	s_waitcnt vmcnt(6)
	v_lshlrev_b32_e32 v94, 16, v138
	v_and_b32_e32 v95, 0xffff0000, v138
	v_lshlrev_b32_e32 v96, 16, v139
	v_and_b32_e32 v97, 0xffff0000, v139
	v_cvt_pk_bf16_f32 v93, v98, v99
	v_lshlrev_b32_e32 v98, 16, v140
	v_and_b32_e32 v99, 0xffff0000, v140
	v_pk_add_f32 v[88:89], v[88:89], v[96:97]
	v_pk_add_f32 v[86:87], v[86:87], v[94:95]
	v_cvt_pk_bf16_f32 v92, v100, v101
	v_lshlrev_b32_e32 v100, 16, v141
	v_and_b32_e32 v101, 0xffff0000, v141
	v_pk_add_f32 v[96:97], v[82:83], v[98:99]
	v_mul_f32_e32 v82, v87, v87
	v_mul_f32_e32 v83, v89, v89
	v_pk_add_f32 v[94:95], v[84:85], v[100:101]
	v_fmac_f32_e32 v82, v86, v86
	v_fmac_f32_e32 v83, v88, v88
	v_add_f32_e32 v82, v82, v83
	v_mul_f32_e32 v83, v97, v97
	v_mul_f32_e32 v84, v95, v95
	v_fmac_f32_e32 v83, v96, v96
	v_fmac_f32_e32 v84, v94, v94
	v_add_f32_e32 v83, v83, v84
	v_add_f32_e32 v82, v82, v83
	v_add_f32_e32 v85, v102, v82
	ds_bpermute_b32 v100, v191, v85
	v_lshl_add_u64 v[82:83], s[36:37], 0, v[180:181]
	v_lshl_add_u64 v[98:99], v[168:169], 1, v[82:83]
	v_cvt_pk_bf16_f32 v84, v86, v87
	v_cvt_pk_bf16_f32 v86, v96, v97
	s_waitcnt lgkmcnt(0)
	v_add_f32_e32 v82, v85, v100
	ds_bpermute_b32 v83, v190, v82
	v_cvt_pk_bf16_f32 v85, v88, v89
	v_cvt_pk_bf16_f32 v87, v94, v95
	global_store_dwordx4 v[98:99], v[90:93], off
	global_store_dwordx4 v[98:99], v[84:87], off offset:256
	s_waitcnt lgkmcnt(0)
	v_add_f32_e32 v212, v82, v83
	s_waitcnt vmcnt(7)
	v_lshlrev_b32_e32 v82, 16, v134
	s_waitcnt lgkmcnt(0)
	v_and_b32_e32 v83, 0xffff0000, v134
	v_lshlrev_b32_e32 v84, 16, v135
	v_and_b32_e32 v85, 0xffff0000, v135
	v_lshlrev_b32_e32 v86, 16, v136
	v_and_b32_e32 v87, 0xffff0000, v136
	v_pk_add_f32 v[78:79], v[78:79], v[82:83]
	v_pk_add_f32 v[80:81], v[80:81], v[84:85]
	v_pk_add_f32 v[84:85], v[74:75], v[86:87]
	v_cvt_pk_bf16_f32 v74, v78, v79
	v_mul_f32_e32 v79, v79, v79
	v_lshlrev_b32_e32 v88, 16, v137
	v_and_b32_e32 v89, 0xffff0000, v137
	v_fmac_f32_e32 v79, v78, v78
	v_mul_f32_e32 v78, v81, v81
	v_pk_add_f32 v[82:83], v[76:77], v[88:89]
	v_fmac_f32_e32 v78, v80, v80
	v_cvt_pk_bf16_f32 v75, v80, v81
	v_add_f32_e32 v78, v79, v78
	v_mul_f32_e32 v79, v85, v85
	v_mul_f32_e32 v80, v83, v83
	v_fmac_f32_e32 v79, v84, v84
	v_fmac_f32_e32 v80, v82, v82
	v_add_f32_e32 v79, v79, v80
	v_add_f32_e32 v86, v78, v79
	s_waitcnt vmcnt(6)
	v_lshlrev_b32_e32 v78, 16, v130
	v_and_b32_e32 v79, 0xffff0000, v130
	v_lshlrev_b32_e32 v80, 16, v131
	v_and_b32_e32 v81, 0xffff0000, v131
	v_cvt_pk_bf16_f32 v77, v82, v83
	v_lshlrev_b32_e32 v82, 16, v132
	v_and_b32_e32 v83, 0xffff0000, v132
	v_pk_add_f32 v[72:73], v[72:73], v[80:81]
	v_pk_add_f32 v[70:71], v[70:71], v[78:79]
	v_cvt_pk_bf16_f32 v76, v84, v85
	v_lshlrev_b32_e32 v84, 16, v133
	v_and_b32_e32 v85, 0xffff0000, v133
	v_pk_add_f32 v[80:81], v[66:67], v[82:83]
	v_mul_f32_e32 v66, v71, v71
	v_mul_f32_e32 v67, v73, v73
	v_pk_add_f32 v[78:79], v[68:69], v[84:85]
	v_fmac_f32_e32 v66, v70, v70
	v_fmac_f32_e32 v67, v72, v72
	v_add_f32_e32 v66, v66, v67
	v_mul_f32_e32 v67, v81, v81
	v_mul_f32_e32 v68, v79, v79
	v_fmac_f32_e32 v67, v80, v80
	v_fmac_f32_e32 v68, v78, v78
	v_add_f32_e32 v67, v67, v68
	v_add_f32_e32 v66, v66, v67
	v_add_f32_e32 v69, v86, v66
	ds_bpermute_b32 v84, v191, v69
	v_lshl_add_u64 v[66:67], s[36:37], 0, v[176:177]
	v_lshl_add_u64 v[82:83], v[168:169], 1, v[66:67]
	v_cvt_pk_bf16_f32 v68, v70, v71
	v_cvt_pk_bf16_f32 v70, v80, v81
	s_waitcnt lgkmcnt(0)
	v_add_f32_e32 v66, v69, v84
	ds_bpermute_b32 v67, v190, v66
	v_cvt_pk_bf16_f32 v69, v72, v73
	v_cvt_pk_bf16_f32 v71, v78, v79
	global_store_dwordx4 v[82:83], v[74:77], off
	global_store_dwordx4 v[82:83], v[68:71], off offset:256
	s_waitcnt lgkmcnt(0)
	v_add_f32_e32 v213, v66, v67
	v_and_b32_e32 v214, 1, v187
	v_cmp_ne_u32_e64 s[64:65], 0, v214
	v_and_b32_e32 v214, 2, v187
	v_cmp_ne_u32_e64 s[100:101], 0, v214
	s_nop 1
	v_cndmask_b32_e64 v215, v210, v211, s[64:65]
	v_cndmask_b32_e64 v216, v212, v213, s[64:65]
	v_cndmask_b32_e64 v217, v215, v216, s[100:101]
	v_lshl_add_u32 v220, v187, 4, v172
	v_ashrrev_i32_e32 v221, 31, v220
	s_lshl_b32 s66, s42, 2
	v_lshlrev_b64 v[66:67], 6, v[220:221]
	s_ashr_i32 s67, s66, 31
	v_lshl_add_u64 v[66:67], s[4:5], 0, v[66:67]
	v_lshl_add_u64 v[66:67], s[66:67], 2, v[66:67]
	s_lshl_b32 s86, s29, 2
	v_lshl_add_u64 v[66:67], v[66:67], 0, s[86:87]
	global_store_dword v[66:67], v217, off
	v_add_u32_e32 v102, 0x80, v172
	v_ashrrev_i32_e32 v103, 31, v102
	v_lshlrev_b64 v[112:113], 11, v[102:103]
	s_waitcnt lgkmcnt(0)
; __device__ __forceinline__ float shx(float v, int lane, int o) { return __int_as_float(__builtin_amdgcn_ds_bpermute((lane ^ o) << 2, __float_as_int(v))); }
; __device__ __forceinline__ u32x4 pack8(const f32x4 a, const f32x4 b) { u32x4 w; w.x = cvt_pk_bf16(a[0], a[1]); w.y = cvt_pk_bf16(a[2], a[3]); w.z = cvt_pk_bf16(b[0], b[1]); w.w = cvt_pk_bf16(b[2], b[3]); return w; }
; __device__ __forceinline__ void unpack8(const u32x4 w, f32x4& a, f32x4& b) { a = (f32x4){bflo(w.x), bfhi(w.x), bflo(w.y), bfhi(w.y)}; b = (f32x4){bflo(w.z), bfhi(w.z), bflo(w.w), bfhi(w.w)}; }
;     __device__ __forceinline__ void operator()(const Acc& acc, const Unit& u, int wr, int wc, int fr, int fq) const {
;     ...
;         for (int ai = 0; ai < 2; ++ai) {
;             u32x4 hv[4][2];
; #pragma unroll
;             for (int m = 0; m < 4; ++m)
; #pragma unroll
;                 for (int bj = 0; bj < 2; ++bj) hv[m][bj] = *(const u32x4*)(hb + (size_t)(row0 + ai * 128 + m * 16) * DM + col0 + bj * 128);
; #pragma unroll
;             for (int m = 0; m < 4; ++m) { const size_t row = (size_t)(row0 + ai * 128 + m * 16); float sq = 0.f;
; #pragma unroll
;                 for (int bj = 0; bj < 2; ++bj) { f32x4 o0, o1; unpack8(hv[m][bj], o0, o1); o0 += acc[ai][bj][m][0] * sc; o1 += acc[ai][bj][m][1] * sc;
;                     *(u32x4*)(hb + row * DM + col0 + bj * 128) = pack8(o0, o1);
;                     sq += ((o0[0] * o0[0] + o0[1] * o0[1]) + (o0[2] * o0[2] + o0[3] * o0[3])) + ((o1[0] * o1[0] + o1[1] * o1[1]) + (o1[2] * o1[2] + o1[3] * o1[3])); }
;                 const int lane = fq * 16 + fr; sq += shx(sq, lane, 16); sq += shx(sq, lane, 32);
;                 if (fq == 0) ssq[row * 16 + u.pn * 4 + wc] = sq; } }
	v_lshl_add_u64 v[66:67], v[170:171], 0, v[112:113]
	global_load_dwordx4 v[104:107], v[66:67], off
	global_load_dwordx4 v[108:111], v[66:67], off offset:256
	v_add_u32_e32 v98, 0x90, v172
	v_ashrrev_i32_e32 v99, 31, v98
	v_add_u32_e32 v94, 0xa0, v172
	v_lshlrev_b64 v[100:101], 11, v[98:99]
	v_ashrrev_i32_e32 v95, 31, v94
	v_add_u32_e32 v90, 0xb0, v172
	v_lshl_add_u64 v[66:67], v[170:171], 0, v[100:101]
	v_lshlrev_b64 v[96:97], 11, v[94:95]
	v_ashrrev_i32_e32 v91, 31, v90
	global_load_dwordx4 v[86:89], v[66:67], off
	global_load_dwordx4 v[82:85], v[66:67], off offset:256
	v_lshl_add_u64 v[66:67], v[170:171], 0, v[96:97]
	v_lshlrev_b64 v[92:93], 11, v[90:91]
	global_load_dwordx4 v[78:81], v[66:67], off
	global_load_dwordx4 v[74:77], v[66:67], off offset:256
	v_lshl_add_u64 v[66:67], v[170:171], 0, v[92:93]
	global_load_dwordx4 v[70:73], v[66:67], off
	s_nop 0
	global_load_dwordx4 v[66:69], v[66:67], off offset:256
	v_lshl_add_u64 v[112:113], s[36:37], 0, v[112:113]
	v_lshl_add_u64 v[112:113], v[168:169], 1, v[112:113]
	s_waitcnt vmcnt(7)
	v_lshlrev_b32_e32 v114, 16, v104
	v_and_b32_e32 v115, 0xffff0000, v104
	v_lshlrev_b32_e32 v104, 16, v105
	v_and_b32_e32 v105, 0xffff0000, v105
	v_lshlrev_b32_e32 v116, 16, v106
	v_and_b32_e32 v117, 0xffff0000, v106
	v_lshlrev_b32_e32 v106, 16, v107
	v_and_b32_e32 v107, 0xffff0000, v107
	v_pk_add_f32 v[64:65], v[64:65], v[104:105]
	v_pk_add_f32 v[62:63], v[62:63], v[114:115]
	v_pk_add_f32 v[104:105], v[60:61], v[106:107]
	v_pk_add_f32 v[106:107], v[58:59], v[116:117]
	v_cvt_pk_bf16_f32 v58, v62, v63
	v_cvt_pk_bf16_f32 v59, v64, v65
	v_cvt_pk_bf16_f32 v60, v106, v107
	v_cvt_pk_bf16_f32 v61, v104, v105
	global_store_dwordx4 v[112:113], v[58:61], off
	s_nop 1
	v_mul_f32_e32 v58, v63, v63
	v_mul_f32_e32 v59, v65, v65
	v_fmac_f32_e32 v58, v62, v62
	v_fmac_f32_e32 v59, v64, v64
	v_add_f32_e32 v58, v58, v59
	v_mul_f32_e32 v59, v107, v107
	v_mul_f32_e32 v60, v105, v105
	v_fmac_f32_e32 v59, v106, v106
	v_fmac_f32_e32 v60, v104, v104
	v_add_f32_e32 v59, v59, v60
	v_add_f32_e32 v104, v58, v59
	s_waitcnt vmcnt(7)
	v_lshlrev_b32_e32 v58, 16, v108
	v_and_b32_e32 v59, 0xffff0000, v108
	v_lshlrev_b32_e32 v60, 16, v109
	v_and_b32_e32 v61, 0xffff0000, v109
	v_lshlrev_b32_e32 v62, 16, v110
	v_and_b32_e32 v63, 0xffff0000, v110
	v_lshlrev_b32_e32 v64, 16, v111
	v_and_b32_e32 v65, 0xffff0000, v111
	v_pk_add_f32 v[56:57], v[56:57], v[60:61]
	v_pk_add_f32 v[54:55], v[54:55], v[58:59]
	v_pk_add_f32 v[58:59], v[52:53], v[64:65]
	v_pk_add_f32 v[60:61], v[50:51], v[62:63]
	v_cvt_pk_bf16_f32 v50, v54, v55
	v_cvt_pk_bf16_f32 v51, v56, v57
	v_cvt_pk_bf16_f32 v52, v60, v61
	v_cvt_pk_bf16_f32 v53, v58, v59
	global_store_dwordx4 v[112:113], v[50:53], off offset:256
	s_nop 1
	v_mul_f32_e32 v50, v55, v55
	v_mul_f32_e32 v51, v57, v57
	v_fmac_f32_e32 v50, v54, v54
	v_fmac_f32_e32 v51, v56, v56
	v_add_f32_e32 v50, v50, v51
	v_mul_f32_e32 v51, v61, v61
	v_mul_f32_e32 v52, v59, v59
	v_fmac_f32_e32 v51, v60, v60
	v_fmac_f32_e32 v52, v58, v58
	v_add_f32_e32 v51, v51, v52
	v_add_f32_e32 v50, v50, v51
	v_add_f32_e32 v50, v104, v50
	ds_bpermute_b32 v51, v191, v50
	s_waitcnt lgkmcnt(0)
	v_add_f32_e32 v50, v50, v51
	ds_bpermute_b32 v51, v190, v50
	s_waitcnt lgkmcnt(0)
	v_add_f32_e32 v210, v50, v51
	s_waitcnt vmcnt(7)
	v_lshlrev_b32_e32 v50, 16, v86
	s_waitcnt lgkmcnt(0)
	v_and_b32_e32 v51, 0xffff0000, v86
	v_lshlrev_b32_e32 v52, 16, v87
	v_and_b32_e32 v53, 0xffff0000, v87
	v_lshlrev_b32_e32 v54, 16, v88
	v_and_b32_e32 v55, 0xffff0000, v88
	v_pk_add_f32 v[46:47], v[46:47], v[50:51]
	v_pk_add_f32 v[48:49], v[48:49], v[52:53]
	v_pk_add_f32 v[52:53], v[42:43], v[54:55]
	v_cvt_pk_bf16_f32 v42, v46, v47
	v_mul_f32_e32 v47, v47, v47
	v_lshlrev_b32_e32 v56, 16, v89
	v_and_b32_e32 v57, 0xffff0000, v89
	v_fmac_f32_e32 v47, v46, v46
	v_mul_f32_e32 v46, v49, v49
	v_pk_add_f32 v[50:51], v[44:45], v[56:57]
	v_fmac_f32_e32 v46, v48, v48
	v_cvt_pk_bf16_f32 v43, v48, v49
	v_add_f32_e32 v46, v47, v46
	v_mul_f32_e32 v47, v53, v53
	v_mul_f32_e32 v48, v51, v51
	v_fmac_f32_e32 v47, v52, v52
	v_fmac_f32_e32 v48, v50, v50
	v_add_f32_e32 v47, v47, v48
	v_add_f32_e32 v54, v46, v47
	s_waitcnt vmcnt(6)
	v_lshlrev_b32_e32 v46, 16, v82
	v_and_b32_e32 v47, 0xffff0000, v82
	v_lshlrev_b32_e32 v48, 16, v83
	v_and_b32_e32 v49, 0xffff0000, v83
	v_cvt_pk_bf16_f32 v45, v50, v51
	v_lshlrev_b32_e32 v50, 16, v84
	v_and_b32_e32 v51, 0xffff0000, v84
	v_pk_add_f32 v[40:41], v[40:41], v[48:49]
	v_pk_add_f32 v[38:39], v[38:39], v[46:47]
	v_cvt_pk_bf16_f32 v44, v52, v53
	v_lshlrev_b32_e32 v52, 16, v85
	v_and_b32_e32 v53, 0xffff0000, v85
	v_pk_add_f32 v[48:49], v[34:35], v[50:51]
	v_mul_f32_e32 v34, v39, v39
	v_mul_f32_e32 v35, v41, v41
	v_pk_add_f32 v[46:47], v[36:37], v[52:53]
	v_fmac_f32_e32 v34, v38, v38
	v_fmac_f32_e32 v35, v40, v40
	v_add_f32_e32 v34, v34, v35
	v_mul_f32_e32 v35, v49, v49
	v_mul_f32_e32 v36, v47, v47
	v_fmac_f32_e32 v35, v48, v48
	v_fmac_f32_e32 v36, v46, v46
	v_add_f32_e32 v35, v35, v36
	v_add_f32_e32 v34, v34, v35
	v_add_f32_e32 v37, v54, v34
	ds_bpermute_b32 v52, v191, v37
	v_lshl_add_u64 v[34:35], s[36:37], 0, v[100:101]
	v_lshl_add_u64 v[50:51], v[168:169], 1, v[34:35]
	v_cvt_pk_bf16_f32 v36, v38, v39
	v_cvt_pk_bf16_f32 v38, v48, v49
	s_waitcnt lgkmcnt(0)
; __device__ __forceinline__ float shx(float v, int lane, int o) { return __int_as_float(__builtin_amdgcn_ds_bpermute((lane ^ o) << 2, __float_as_int(v))); }
; __device__ __forceinline__ u32x4 pack8(const f32x4 a, const f32x4 b) { u32x4 w; w.x = cvt_pk_bf16(a[0], a[1]); w.y = cvt_pk_bf16(a[2], a[3]); w.z = cvt_pk_bf16(b[0], b[1]); w.w = cvt_pk_bf16(b[2], b[3]); return w; }
; __device__ __forceinline__ void unpack8(const u32x4 w, f32x4& a, f32x4& b) { a = (f32x4){bflo(w.x), bfhi(w.x), bflo(w.y), bfhi(w.y)}; b = (f32x4){bflo(w.z), bfhi(w.z), bflo(w.w), bfhi(w.w)}; }
;     __device__ __forceinline__ void operator()(const Acc& acc, const Unit& u, int wr, int wc, int fr, int fq) const {
;     ...
;             for (int m = 0; m < 4; ++m) { const size_t row = (size_t)(row0 + ai * 128 + m * 16); float sq = 0.f;
; #pragma unroll
;                 for (int bj = 0; bj < 2; ++bj) { f32x4 o0, o1; unpack8(hv[m][bj], o0, o1); o0 += acc[ai][bj][m][0] * sc; o1 += acc[ai][bj][m][1] * sc;
;                     *(u32x4*)(hb + row * DM + col0 + bj * 128) = pack8(o0, o1);
;                     sq += ((o0[0] * o0[0] + o0[1] * o0[1]) + (o0[2] * o0[2] + o0[3] * o0[3])) + ((o1[0] * o1[0] + o1[1] * o1[1]) + (o1[2] * o1[2] + o1[3] * o1[3])); }
;                 const int lane = fq * 16 + fr; sq += shx(sq, lane, 16); sq += shx(sq, lane, 32);
;                 if (fq == 0) ssq[row * 16 + u.pn * 4 + wc] = sq; } }
	v_add_f32_e32 v34, v37, v52
	ds_bpermute_b32 v35, v190, v34
	v_cvt_pk_bf16_f32 v37, v40, v41
	v_cvt_pk_bf16_f32 v39, v46, v47
	global_store_dwordx4 v[50:51], v[42:45], off
	global_store_dwordx4 v[50:51], v[36:39], off offset:256
	s_waitcnt lgkmcnt(0)
	v_add_f32_e32 v211, v34, v35
	s_waitcnt vmcnt(7)
	v_lshlrev_b32_e32 v34, 16, v78
	s_waitcnt lgkmcnt(0)
	v_and_b32_e32 v35, 0xffff0000, v78
	v_lshlrev_b32_e32 v36, 16, v79
	v_and_b32_e32 v37, 0xffff0000, v79
	v_lshlrev_b32_e32 v38, 16, v80
	v_and_b32_e32 v39, 0xffff0000, v80
	v_pk_add_f32 v[30:31], v[30:31], v[34:35]
	v_pk_add_f32 v[32:33], v[32:33], v[36:37]
	v_pk_add_f32 v[36:37], v[26:27], v[38:39]
	v_cvt_pk_bf16_f32 v26, v30, v31
	v_mul_f32_e32 v31, v31, v31
	v_lshlrev_b32_e32 v40, 16, v81
	v_and_b32_e32 v41, 0xffff0000, v81
	v_fmac_f32_e32 v31, v30, v30
	v_mul_f32_e32 v30, v33, v33
	v_pk_add_f32 v[34:35], v[28:29], v[40:41]
	v_fmac_f32_e32 v30, v32, v32
	v_cvt_pk_bf16_f32 v27, v32, v33
	v_add_f32_e32 v30, v31, v30
	v_mul_f32_e32 v31, v37, v37
	v_mul_f32_e32 v32, v35, v35
	v_fmac_f32_e32 v31, v36, v36
	v_fmac_f32_e32 v32, v34, v34
	v_add_f32_e32 v31, v31, v32
	v_add_f32_e32 v38, v30, v31
	s_waitcnt vmcnt(6)
	v_lshlrev_b32_e32 v30, 16, v74
	v_and_b32_e32 v31, 0xffff0000, v74
	v_lshlrev_b32_e32 v32, 16, v75
	v_and_b32_e32 v33, 0xffff0000, v75
	v_cvt_pk_bf16_f32 v29, v34, v35
	v_lshlrev_b32_e32 v34, 16, v76
	v_and_b32_e32 v35, 0xffff0000, v76
	v_pk_add_f32 v[24:25], v[24:25], v[32:33]
	v_pk_add_f32 v[22:23], v[22:23], v[30:31]
	v_cvt_pk_bf16_f32 v28, v36, v37
	v_lshlrev_b32_e32 v36, 16, v77
	v_and_b32_e32 v37, 0xffff0000, v77
	v_pk_add_f32 v[32:33], v[18:19], v[34:35]
	v_mul_f32_e32 v18, v23, v23
	v_mul_f32_e32 v19, v25, v25
	v_pk_add_f32 v[30:31], v[20:21], v[36:37]
	v_fmac_f32_e32 v18, v22, v22
	v_fmac_f32_e32 v19, v24, v24
	v_add_f32_e32 v18, v18, v19
	v_mul_f32_e32 v19, v33, v33
	v_mul_f32_e32 v20, v31, v31
	v_fmac_f32_e32 v19, v32, v32
	v_fmac_f32_e32 v20, v30, v30
	v_add_f32_e32 v19, v19, v20
	v_add_f32_e32 v18, v18, v19
	v_add_f32_e32 v21, v38, v18
	ds_bpermute_b32 v36, v191, v21
	v_lshl_add_u64 v[18:19], s[36:37], 0, v[96:97]
	v_lshl_add_u64 v[34:35], v[168:169], 1, v[18:19]
	v_cvt_pk_bf16_f32 v20, v22, v23
	v_cvt_pk_bf16_f32 v22, v32, v33
	s_waitcnt lgkmcnt(0)
	v_add_f32_e32 v18, v21, v36
	ds_bpermute_b32 v19, v190, v18
	v_cvt_pk_bf16_f32 v21, v24, v25
	v_cvt_pk_bf16_f32 v23, v30, v31
	global_store_dwordx4 v[34:35], v[26:29], off
	global_store_dwordx4 v[34:35], v[20:23], off offset:256
	s_waitcnt lgkmcnt(0)
	v_add_f32_e32 v212, v18, v19
	s_waitcnt vmcnt(7)
	v_lshlrev_b32_e32 v18, 16, v70
	s_waitcnt lgkmcnt(0)
	v_and_b32_e32 v19, 0xffff0000, v70
	v_lshlrev_b32_e32 v20, 16, v71
	v_and_b32_e32 v21, 0xffff0000, v71
	v_lshlrev_b32_e32 v22, 16, v72
	v_and_b32_e32 v23, 0xffff0000, v72
	v_pk_add_f32 v[14:15], v[14:15], v[18:19]
	v_pk_add_f32 v[16:17], v[16:17], v[20:21]
	v_pk_add_f32 v[20:21], v[10:11], v[22:23]
	v_cvt_pk_bf16_f32 v10, v14, v15
	v_mul_f32_e32 v15, v15, v15
	v_lshlrev_b32_e32 v24, 16, v73
	v_and_b32_e32 v25, 0xffff0000, v73
	v_fmac_f32_e32 v15, v14, v14
	v_mul_f32_e32 v14, v17, v17
	v_pk_add_f32 v[18:19], v[12:13], v[24:25]
	v_fmac_f32_e32 v14, v16, v16
	v_cvt_pk_bf16_f32 v11, v16, v17
	v_add_f32_e32 v14, v15, v14
	v_mul_f32_e32 v15, v21, v21
	v_mul_f32_e32 v16, v19, v19
	v_fmac_f32_e32 v15, v20, v20
	v_fmac_f32_e32 v16, v18, v18
	v_add_f32_e32 v15, v15, v16
	v_add_f32_e32 v22, v14, v15
	s_waitcnt vmcnt(6)
	v_lshlrev_b32_e32 v14, 16, v66
	v_and_b32_e32 v15, 0xffff0000, v66
	v_lshlrev_b32_e32 v16, 16, v67
	v_and_b32_e32 v17, 0xffff0000, v67
	v_cvt_pk_bf16_f32 v13, v18, v19
	v_lshlrev_b32_e32 v18, 16, v68
	v_and_b32_e32 v19, 0xffff0000, v68
	v_pk_add_f32 v[8:9], v[8:9], v[16:17]
	v_pk_add_f32 v[6:7], v[6:7], v[14:15]
	v_cvt_pk_bf16_f32 v12, v20, v21
	v_lshlrev_b32_e32 v20, 16, v69
	v_and_b32_e32 v21, 0xffff0000, v69
	v_pk_add_f32 v[16:17], v[2:3], v[18:19]
	v_mul_f32_e32 v2, v7, v7
	v_mul_f32_e32 v3, v9, v9
	v_pk_add_f32 v[14:15], v[4:5], v[20:21]
	v_fmac_f32_e32 v2, v6, v6
	v_fmac_f32_e32 v3, v8, v8
	v_add_f32_e32 v2, v2, v3
	v_mul_f32_e32 v3, v17, v17
	v_mul_f32_e32 v4, v15, v15
	v_fmac_f32_e32 v3, v16, v16
	v_fmac_f32_e32 v4, v14, v14
	v_add_f32_e32 v3, v3, v4
	v_add_f32_e32 v2, v2, v3
	v_add_f32_e32 v5, v22, v2
	ds_bpermute_b32 v20, v191, v5
	v_lshl_add_u64 v[2:3], s[36:37], 0, v[92:93]
	v_lshl_add_u64 v[18:19], v[168:169], 1, v[2:3]
	v_cvt_pk_bf16_f32 v4, v6, v7
	v_cvt_pk_bf16_f32 v6, v16, v17
	s_waitcnt lgkmcnt(0)
	v_add_f32_e32 v2, v5, v20
	ds_bpermute_b32 v3, v190, v2
	v_cvt_pk_bf16_f32 v5, v8, v9
	v_cvt_pk_bf16_f32 v7, v14, v15
	global_store_dwordx4 v[18:19], v[10:13], off
	global_store_dwordx4 v[18:19], v[4:7], off offset:256
	s_waitcnt lgkmcnt(0)
	v_add_f32_e32 v213, v2, v3
	v_and_b32_e32 v214, 1, v187
	v_cmp_ne_u32_e64 s[64:65], 0, v214
	v_and_b32_e32 v214, 2, v187
	v_cmp_ne_u32_e64 s[100:101], 0, v214
	s_nop 1
	v_cndmask_b32_e64 v215, v210, v211, s[64:65]
	v_cndmask_b32_e64 v216, v212, v213, s[64:65]
	v_cndmask_b32_e64 v217, v215, v216, s[100:101]
	v_lshl_add_u32 v220, v187, 4, v172
	v_add_u32_e32 v220, 0x80, v220
	v_ashrrev_i32_e32 v221, 31, v220
	s_lshl_b32 s66, s42, 2
	v_lshlrev_b64 v[2:3], 6, v[220:221]
	s_ashr_i32 s67, s66, 31
	v_lshl_add_u64 v[2:3], s[4:5], 0, v[2:3]
	v_lshl_add_u64 v[2:3], s[66:67], 2, v[2:3]
	s_lshl_b32 s86, s29, 2
	v_lshl_add_u64 v[2:3], v[2:3], 0, s[86:87]
	global_store_dword v[2:3], v217, off
	s_branch .LBB0_197
